# hg_scan: next chunk staged by LDS-DMA into a second LDS buffer (one barrier per chunk, no ds_write staging)
# baseline (speedup 1.0000x reference)
; DI int opaque_tid() { int t = threadIdx.x; asm volatile("" : "+v"(t)); return t; }
; DI void hg_scan_block(const Params& p, int chain_in, unsigned char* smem) {
;     ...
;   const int tid = opaque_tid(), lane = tid & 63, sl = tid >> 6, l31 = lane & 31, h = lane >> 5;
;   const int hd = chain & 3, b = (chain >> 2) & 3, dir = chain >> 4;
;   float* OHG = (float*)(WS_ + O_OHG) + (size_t)dir * NTOK * 512;
;   bfr* sU = (bfr*)smem;
;   const bfr *s_qhat = sU, *s_khT = sU + 4096, *s_vT = sU + 8192;
;   float* s_ds = (float*)(smem + 24576);
;   const u32x4* src = (const u32x4*)(WS_ + O_HGU) + (size_t)chain * 136 * 1536;
;   const float* dsg = (const float*)(WS_ + O_HGD) + (size_t)chain * 136 * 128;
;   u32x4 st[6]; float dsr;
; #pragma unroll
;   for (int i = 0; i < 6; ++i) st[i] = src[tid + 256 * i];
;   dsr = dsg[tid & 127];
.LBB0_494:
	s_or_b64 exec, exec, s[4:5]
	v_readlane_b32 s6, v255, 1
	v_readlane_b32 s7, v255, 2
	v_mov_b32_e32 v211, v216
	s_mov_b64 s[4:5], -1
	s_and_b64 vcc, exec, s[6:7]
	s_mov_b32 s37, 0x800000
	s_barrier
	s_cbranch_vccz .LBB0_505
	v_readlane_b32 s4, v255, 35
	v_readlane_b32 s5, v255, 36
	s_andn2_b64 vcc, exec, s[4:5]
	s_cbranch_vccnz .LBB0_504
	v_lshrrev_b32_e32 v165, 6, v216
	v_lshlrev_b32_e32 v165, 10, v165
	s_nop 0
	v_readfirstlane_b32 s38, v165
	s_mov_b32 s39, 0x8000
	v_readlane_b32 s4, v254, 28
	s_nop 1
	v_mov_b32_e32 v0, s4
	s_mov_b64 s[4:5], s[84:85]
	v_readfirstlane_b32 s8, v0
	s_sub_i32 s9, s8, 32
	s_ashr_i32 s6, s9, 4
	s_mul_hi_i32 s10, s6, 0x2200000
	s_mul_i32 s11, s6, 0x2200000
	s_mul_i32 s6, s9, 0x330000
	v_mov_b32_e32 v0, v216
	s_mul_hi_i32 s7, s9, 0x330000
	s_add_u32 s6, s4, s6
	s_addc_u32 s7, s5, s7
	v_ashrrev_i32_e32 v1, 31, v0
	v_lshl_add_u64 v[104:105], v[0:1], 4, s[6:7]
	s_mov_b32 s6, 0x619cf000
	v_add_co_u32_e32 v2, vcc, s6, v104
	s_mov_b32 s6, 0x619d0000
	s_nop 0
	v_addc_co_u32_e32 v3, vcc, 0, v105, vcc
	v_add_co_u32_e32 v4, vcc, s6, v104
	s_mov_b32 s6, 0x619d1000
	s_nop 0
	v_addc_co_u32_e32 v5, vcc, 0, v105, vcc
	v_add_u32_e32 v164, 0x0, v165
	v_add_co_u32_e32 v162, vcc, 0x600, v2
	v_readfirstlane_b32 s28, v164
	s_nop 0
	v_addc_co_u32_e32 v163, vcc, 0, v3, vcc
	s_mov_b32 m0, s28
	s_nop 0
	global_load_lds_dwordx4 v[162:163], off
	v_add_u32_e32 v164, 0x1000, v165
	v_add_co_u32_e32 v162, vcc, 0x600, v4
	v_readfirstlane_b32 s28, v164
	s_nop 0
	v_addc_co_u32_e32 v163, vcc, 0, v5, vcc
	s_mov_b32 m0, s28
	s_nop 0
	global_load_lds_dwordx4 v[162:163], off
	v_add_co_u32_e32 v2, vcc, s6, v104
	s_mov_b32 s6, 0x619d2000
	s_nop 0
	v_addc_co_u32_e32 v3, vcc, 0, v105, vcc
	v_add_co_u32_e32 v4, vcc, s6, v104
	s_mov_b32 s6, 0x619d3000
	s_nop 0
	v_addc_co_u32_e32 v5, vcc, 0, v105, vcc
	v_add_u32_e32 v164, 0x2000, v165
	v_add_co_u32_e32 v162, vcc, 0x600, v2
	v_readfirstlane_b32 s28, v164
	s_nop 0
	v_addc_co_u32_e32 v163, vcc, 0, v3, vcc
	s_mov_b32 m0, s28
	s_nop 0
	global_load_lds_dwordx4 v[162:163], off
	v_add_u32_e32 v164, 0x3000, v165
	v_add_co_u32_e32 v162, vcc, 0x600, v4
	v_readfirstlane_b32 s28, v164
	s_nop 0
	v_addc_co_u32_e32 v163, vcc, 0, v5, vcc
	s_mov_b32 m0, s28
	s_nop 0
	global_load_lds_dwordx4 v[162:163], off
	v_add_co_u32_e32 v2, vcc, s6, v104
	s_bfe_u32 s22, s8, 0x20002
	s_nop 0
	v_addc_co_u32_e32 v3, vcc, 0, v105, vcc
	s_mov_b32 s6, 0x619d4000
	s_add_u32 s11, s4, s11
	s_mul_i32 s21, s9, 0x11000
	v_add_co_u32_e32 v4, vcc, s6, v104
	s_addc_u32 s10, s5, s10
	s_mul_hi_i32 s20, s9, 0x11000
	v_addc_co_u32_e32 v5, vcc, 0, v105, vcc
	v_add_u32_e32 v164, 0x4000, v165
	v_add_co_u32_e32 v162, vcc, 0x600, v2
	v_readfirstlane_b32 s28, v164
	s_nop 0
	v_addc_co_u32_e32 v163, vcc, 0, v3, vcc
	s_mov_b32 m0, s28
	s_nop 0
	global_load_lds_dwordx4 v[162:163], off
	v_add_u32_e32 v164, 0x5000, v165
	v_add_co_u32_e32 v162, vcc, 0x600, v4
	v_readfirstlane_b32 s28, v164
	s_nop 0
	v_addc_co_u32_e32 v163, vcc, 0, v5, vcc
	s_mov_b32 m0, s28
	s_nop 0
	global_load_lds_dwordx4 v[162:163], off
	v_and_b32_e32 v2, 0x7f, v0
	s_add_u32 s4, s4, s21
	v_lshlrev_b32_e32 v208, 2, v2
	s_addc_u32 s5, s5, s20
	v_lshl_add_u64 v[2:3], s[4:5], 0, v[208:209]
	s_mov_b32 s4, 0x67fcf000
	s_cmp_lt_u32 s9, 16
	v_bfe_u32 v21, v0, 5, 1
	v_add_co_u32_e32 v4, vcc, s4, v2
	s_cselect_b64 s[6:7], -1, 0
	s_lshl_b32 s4, s8, 9
	v_ashrrev_i32_e32 v20, 6, v0
	v_lshlrev_b32_e32 v110, 2, v21
	s_and_b32 s4, s4, 0x600
	v_and_b32_e32 v1, 31, v0
	v_xor_b32_e32 v8, 0xff, v110
	v_lshlrev_b32_e32 v6, 5, v20
	s_add_u32 s4, s11, s4
	s_mul_i32 s20, s22, 0x1100
	v_ashrrev_i32_e32 v7, 31, v6
	s_addc_u32 s5, s10, 0
	s_add_u32 s30, s4, 0x681ef600
	s_addc_u32 s31, s5, 0
	v_lshlrev_b32_e32 v208, 2, v1
	v_cndmask_b32_e64 v1, v8, v110, s[6:7]
	v_lshl_add_u64 v[6:7], v[6:7], 2, s[4:5]
	v_or_b32_e32 v1, s20, v1
	v_lshl_add_u64 v[6:7], v[6:7], 0, v[208:209]
	v_lshlrev_b32_e32 v208, 11, v1
	v_or_b32_e32 v1, 1, v110
	v_xor_b32_e32 v8, 0xfe, v110
	s_mov_b64 s[4:5], 0x681ef600
	v_cndmask_b32_e64 v1, v8, v1, s[6:7]
	v_lshl_add_u64 v[106:107], v[6:7], 0, s[4:5]
	v_lshrrev_b32_e32 v160, 6, v216
	v_and_b32_e32 v162, 31, v216
	v_lshlrev_b32_e32 v160, 7, v160
	v_lshlrev_b32_e32 v163, 11, v110
	v_lshl_or_b32 v160, v162, 2, v160
	v_sub_u32_e32 v162, 0xf800, v163
	v_mov_b32_e32 v161, 0x800
	v_cndmask_b32_e64 v163, v162, v163, s[6:7]
	v_mov_b32_e32 v162, 0xfffff800
	v_add_u32_e32 v160, v160, v163
	v_cndmask_b32_e64 v161, v162, v161, s[6:7]
	v_or_b32_e32 v1, s20, v1
	v_lshl_add_u64 v[6:7], v[106:107], 0, v[208:209]
	v_lshlrev_b32_e32 v208, 11, v1
	v_or_b32_e32 v1, 2, v110
	v_xor_b32_e32 v10, 0xfd, v110
	v_cndmask_b32_e64 v1, v10, v1, s[6:7]
	v_or_b32_e32 v1, s20, v1
	v_lshl_add_u64 v[8:9], v[106:107], 0, v[208:209]
	v_lshlrev_b32_e32 v208, 11, v1
	v_or_b32_e32 v1, 3, v110
	v_xor_b32_e32 v12, 0xfc, v110
	v_cndmask_b32_e64 v1, v12, v1, s[6:7]
	v_or_b32_e32 v1, s20, v1
	v_lshl_add_u64 v[10:11], v[106:107], 0, v[208:209]
	v_lshlrev_b32_e32 v208, 11, v1
	v_or_b32_e32 v1, 8, v110
	v_xor_b32_e32 v14, 0xf7, v110
	v_cndmask_b32_e64 v1, v14, v1, s[6:7]
	v_or_b32_e32 v1, s20, v1
	v_lshl_add_u64 v[12:13], v[106:107], 0, v[208:209]
	v_lshlrev_b32_e32 v208, 11, v1
	v_or_b32_e32 v1, 9, v110
	v_xor_b32_e32 v16, 0xf6, v110
	v_cndmask_b32_e64 v1, v16, v1, s[6:7]
	v_or_b32_e32 v1, s20, v1
	v_lshl_add_u64 v[14:15], v[106:107], 0, v[208:209]
	v_lshlrev_b32_e32 v208, 11, v1
	v_or_b32_e32 v1, 10, v110
	v_xor_b32_e32 v18, 0xf5, v110
	v_cndmask_b32_e64 v1, v18, v1, s[6:7]
	v_or_b32_e32 v1, s20, v1
	v_addc_co_u32_e32 v5, vcc, 0, v3, vcc
	v_lshl_add_u64 v[16:17], v[106:107], 0, v[208:209]
	v_lshlrev_b32_e32 v208, 11, v1
; DI int crow(int r, int h) { return (r & 3) + 8 * (r >> 2) + 4 * h; }
; DI f32x16 zero16() { f32x16 z; for (int i = 0; i < 16; ++i) z[i] = 0.f; return z; }
; DI void stream_of(int n, int cpc, int& m, int& T, int& soff) { if (n < cpc) { m = n; T = CTX; soff = 0; } else { m = n - cpc; T = SEQ; soff = CTX; } }
; DI void hg_scan_block(const Params& p, int chain_in, unsigned char* smem) {
;     ...
;   u32x4 st[6]; float dsr;
; #pragma unroll
;   for (int i = 0; i < 6; ++i) st[i] = src[tid + 256 * i];
;   dsr = dsg[tid & 127];
;   float oc[16];
;   {
;     int m0_, T0_, so0_; stream_of(0, 8, m0_, T0_, so0_);
; #pragma unroll
;     for (int r = 0; r < 16; ++r) {
;       const int pos = 32 * m0_ + crow(r, h), t = dir ? T0_ - 1 - pos : pos;
;       oc[r] = OHG[(size_t)(b * SP + so0_ + t) * 512 + hd * 128 + 32 * sl + l31];
;     }
;   }
;   f32x16 S[4];
;   for (int i = 0; i < 4; ++i) S[i] = zero16();
	v_lshl_add_u64 v[18:19], v[106:107], 0, v[208:209]
	global_load_dword v111, v[4:5], off offset:1536
	global_load_dword v148, v[6:7], off
	global_load_dword v147, v[8:9], off
	global_load_dword v144, v[10:11], off
	global_load_dword v142, v[12:13], off
	global_load_dword v140, v[14:15], off
	global_load_dword v138, v[16:17], off
	global_load_dword v137, v[18:19], off
	v_or_b32_e32 v1, 11, v110
	v_xor_b32_e32 v4, 0xf4, v110
	v_cndmask_b32_e64 v1, v4, v1, s[6:7]
	v_or_b32_e32 v1, s20, v1
	v_lshlrev_b32_e32 v208, 11, v1
	v_or_b32_e32 v1, 16, v110
	v_xor_b32_e32 v6, 0xef, v110
	v_cndmask_b32_e64 v1, v6, v1, s[6:7]
	v_or_b32_e32 v1, s20, v1
	v_lshl_add_u64 v[4:5], v[106:107], 0, v[208:209]
	v_lshlrev_b32_e32 v208, 11, v1
	v_or_b32_e32 v1, 17, v110
	v_xor_b32_e32 v8, 0xee, v110
	v_cndmask_b32_e64 v1, v8, v1, s[6:7]
	v_or_b32_e32 v1, s20, v1
	v_lshl_add_u64 v[6:7], v[106:107], 0, v[208:209]
	v_lshlrev_b32_e32 v208, 11, v1
	v_or_b32_e32 v1, 18, v110
	v_xor_b32_e32 v10, 0xed, v110
	v_cndmask_b32_e64 v1, v10, v1, s[6:7]
	v_or_b32_e32 v1, s20, v1
	v_lshl_add_u64 v[8:9], v[106:107], 0, v[208:209]
	v_lshlrev_b32_e32 v208, 11, v1
	v_or_b32_e32 v1, 19, v110
	v_xor_b32_e32 v12, 0xec, v110
	v_cndmask_b32_e64 v1, v12, v1, s[6:7]
	v_or_b32_e32 v1, s20, v1
	v_lshl_add_u64 v[10:11], v[106:107], 0, v[208:209]
	v_lshlrev_b32_e32 v208, 11, v1
	v_or_b32_e32 v1, 24, v110
	v_xor_b32_e32 v14, 0xe7, v110
	v_cndmask_b32_e64 v1, v14, v1, s[6:7]
	v_or_b32_e32 v1, s20, v1
	v_lshl_add_u64 v[12:13], v[106:107], 0, v[208:209]
	v_lshlrev_b32_e32 v208, 11, v1
	v_or_b32_e32 v1, 25, v110
	v_xor_b32_e32 v16, 0xe6, v110
	v_cndmask_b32_e64 v1, v16, v1, s[6:7]
	v_or_b32_e32 v1, s20, v1
	v_lshl_add_u64 v[14:15], v[106:107], 0, v[208:209]
	v_lshlrev_b32_e32 v208, 11, v1
	v_or_b32_e32 v1, 26, v110
	v_xor_b32_e32 v18, 0xe5, v110
	v_cndmask_b32_e64 v1, v18, v1, s[6:7]
	v_or_b32_e32 v1, s20, v1
	v_lshl_add_u64 v[16:17], v[106:107], 0, v[208:209]
	v_lshlrev_b32_e32 v208, 11, v1
	v_lshl_add_u64 v[18:19], v[106:107], 0, v[208:209]
	global_load_dword v146, v[4:5], off
	global_load_dword v145, v[6:7], off
	global_load_dword v143, v[8:9], off
	global_load_dword v141, v[10:11], off
	global_load_dword v139, v[12:13], off
	global_load_dword v136, v[14:15], off
	global_load_dword v135, v[16:17], off
	global_load_dword v133, v[18:19], off
	v_or_b32_e32 v1, 27, v110
	v_xor_b32_e32 v4, 0xe4, v110
	v_cndmask_b32_e64 v1, v4, v1, s[6:7]
	v_or_b32_e32 v1, s20, v1
	v_lshlrev_b32_e32 v208, 11, v1
	v_lshl_add_u64 v[4:5], v[106:107], 0, v[208:209]
	global_load_dword v132, v[4:5], off
	v_and_b32_e32 v1, 63, v0
	s_movk_i32 s4, 0x80
	v_lshlrev_b32_e32 v112, 4, v0
	v_cmp_gt_i32_e64 s[4:5], s4, v0
	v_lshlrev_b32_e32 v113, 4, v1
	v_mul_lo_u32 v1, v0, -12
	s_mov_b64 s[8:9], 0x67fcf800
	v_mov_b32_e32 v0, 0
	s_mov_b32 s21, 0
	v_lshl_or_b32 v114, v20, 11, v113
	v_lshlrev_b32_e32 v115, 4, v21
	v_lshl_add_u64 v[108:109], v[2:3], 0, s[8:9]
	s_mov_b64 s[8:9], 0
	v_add_u32_e32 v116, v112, v1
	v_mov_b32_e32 v1, v0
	v_mov_b32_e32 v2, v0
	v_mov_b32_e32 v3, v0
	v_mov_b32_e32 v4, v0
	v_mov_b32_e32 v5, v0
	v_mov_b32_e32 v6, v0
	v_mov_b32_e32 v7, v0
	v_mov_b32_e32 v8, v0
	v_mov_b32_e32 v9, v0
	v_mov_b32_e32 v10, v0
	v_mov_b32_e32 v11, v0
	v_mov_b32_e32 v12, v0
	v_mov_b32_e32 v13, v0
	v_mov_b32_e32 v14, v0
	v_mov_b32_e32 v15, v0
	v_mov_b32_e32 v16, v0
	v_mov_b32_e32 v17, v0
	v_mov_b32_e32 v18, v0
	v_mov_b32_e32 v19, v0
	v_mov_b32_e32 v20, v0
	v_mov_b32_e32 v21, v0
	v_mov_b32_e32 v22, v0
	v_mov_b32_e32 v23, v0
	v_mov_b32_e32 v24, v0
	v_mov_b32_e32 v25, v0
	v_mov_b32_e32 v26, v0
	v_mov_b32_e32 v27, v0
	v_mov_b32_e32 v28, v0
	v_mov_b32_e32 v29, v0
	v_mov_b32_e32 v30, v0
	v_mov_b32_e32 v31, v0
	v_mov_b32_e32 v32, v0
	v_mov_b32_e32 v33, v0
	v_mov_b32_e32 v34, v0
	v_mov_b32_e32 v35, v0
	v_mov_b32_e32 v36, v0
	v_mov_b32_e32 v37, v0
	v_mov_b32_e32 v38, v0
	v_mov_b32_e32 v39, v0
	v_mov_b32_e32 v40, v0
	v_mov_b32_e32 v41, v0
	v_mov_b32_e32 v42, v0
	v_mov_b32_e32 v43, v0
	v_mov_b32_e32 v44, v0
	v_mov_b32_e32 v45, v0
	v_mov_b32_e32 v46, v0
	v_mov_b32_e32 v47, v0
	v_mov_b32_e32 v48, v0
	v_mov_b32_e32 v49, v0
	v_mov_b32_e32 v50, v0
	v_mov_b32_e32 v51, v0
	v_mov_b32_e32 v52, v0
	v_mov_b32_e32 v53, v0
	v_mov_b32_e32 v54, v0
	v_mov_b32_e32 v55, v0
	v_mov_b32_e32 v56, v0
	v_mov_b32_e32 v57, v0
	v_mov_b32_e32 v58, v0
	v_mov_b32_e32 v59, v0
	v_mov_b32_e32 v60, v0
	v_mov_b32_e32 v61, v0
	v_mov_b32_e32 v62, v0
	v_mov_b32_e32 v63, v0
	s_branch .LBB0_498
; #define MFMA(a, b, c) __builtin_amdgcn_mfma_f32_32x32x16_bf16((a), (b), (c), 0, 0, 0)
; DI int crow(int r, int h) { return (r & 3) + 8 * (r >> 2) + 4 * h; }
; DI f32x16 zero16() { f32x16 z; for (int i = 0; i < 16; ++i) z[i] = 0.f; return z; }
; DI void stream_of(int n, int cpc, int& m, int& T, int& soff) { if (n < cpc) { m = n; T = CTX; soff = 0; } else { m = n - cpc; T = SEQ; soff = CTX; } }
; DI void hg_scan_block(const Params& p, int chain_in, unsigned char* smem) {
;     ...
;     int m, T, soff; stream_of(n, 8, m, T, soff);
;     f32x16 o = zero16();
; #pragma unroll
;     for (int k = 0; k < 4; ++k) {
;       o = MFMA(ld16(s_qhat + ((k * 2 + 0) * 64 + lane) * 8), pack8<0>(S[k]), o);
;       o = MFMA(ld16(s_qhat + ((k * 2 + 1) * 64 + lane) * 8), pack8<1>(S[k]), o);
;     }
; #pragma unroll
;     for (int r = 0; r < 16; ++r) {
;       const int pos = 32 * m + crow(r, h), t = dir ? T - 1 - pos : pos;
;       float* dst = OHG + (size_t)(b * SP + soff + t) * 512 + hd * 128 + 32 * sl + l31;
;       *dst = oc[r] + o[r];
;     }
;     const bf16x8 v0 = ld16(s_vT + ((sl * 2 + 0) * 64 + lane) * 8), v1 = ld16(s_vT + ((sl * 2 + 1) * 64 + lane) * 8);
; #pragma unroll
;     for (int k = 0; k < 4; ++k) {
; #pragma unroll
;       for (int g = 0; g < 4; ++g) {
;         const f32x4 d4 = *(const f32x4*)(s_ds + 32 * k + 8 * g + 4 * h);
;         S[k][4 * g] *= d4[0]; S[k][4 * g + 1] *= d4[1]; S[k][4 * g + 2] *= d4[2]; S[k][4 * g + 3] *= d4[3];
;       }
;       S[k] = MFMA(ld16(s_khT + ((k * 2 + 0) * 64 + lane) * 8), v0, S[k]);
;       S[k] = MFMA(ld16(s_khT + ((k * 2 + 1) * 64 + lane) * 8), v1, S[k]);
.LBB0_497:
	ds_read_b128 v[64:67], v113
	ds_read_b128 v[150:153], v113 offset:1024
	v_cvt_pk_bf16_f32 v68, v48, v49
	v_cvt_pk_bf16_f32 v69, v50, v51
	v_cvt_pk_bf16_f32 v70, v52, v53
	v_cvt_pk_bf16_f32 v71, v54, v55
	v_cvt_pk_bf16_f32 v154, v56, v57
	v_cvt_pk_bf16_f32 v155, v58, v59
	v_cvt_pk_bf16_f32 v156, v60, v61
	s_waitcnt lgkmcnt(0)
	v_mfma_f32_32x32x16_bf16 v[64:79], v[64:67], v[68:71], 0
	v_cvt_pk_bf16_f32 v157, v62, v63
	s_cmp_lt_u32 s21, 8
	s_cselect_b32 s11, 0, -8
	s_cselect_b32 s10, 0x100, s95
	s_cselect_b32 s22, 0, 0x100
	s_add_i32 s11, s11, s21
	s_lshl_b32 s11, s11, 5
	v_mfma_f32_32x32x16_bf16 v[64:79], v[150:153], v[154:157], v[64:79]
	ds_read_b128 v[150:153], v113 offset:2048
	v_cvt_pk_bf16_f32 v154, v32, v33
	v_cvt_pk_bf16_f32 v155, v34, v35
	v_cvt_pk_bf16_f32 v156, v36, v37
	v_cvt_pk_bf16_f32 v157, v38, v39
	s_add_i32 s22, s22, s20
	s_add_i32 s26, s22, s11
	s_sub_i32 s27, s10, s11
	s_add_i32 s27, s27, s22
	s_sub_i32 s27, s27, 32
	s_cmp_lg_u64 s[6:7], 0
	s_cselect_b32 s26, s26, s27
	s_lshl_b32 s26, s26, 11
	s_add_u32 s34, s30, s26
	s_addc_u32 s35, s31, 0
	s_add_u32 s8, s8, 0x6000
	s_addc_u32 s9, s9, 0
	s_waitcnt lgkmcnt(0)
	v_mfma_f32_32x32x16_bf16 v[64:79], v[150:153], v[154:157], v[64:79]
	ds_read_b128 v[150:153], v113 offset:3072
	v_cvt_pk_bf16_f32 v154, v40, v41
	v_cvt_pk_bf16_f32 v155, v42, v43
	v_cvt_pk_bf16_f32 v156, v44, v45
	v_cvt_pk_bf16_f32 v157, v46, v47
	s_add_i32 s21, s21, 1
	s_cmp_lg_u32 s8, 0x330000
	s_waitcnt lgkmcnt(0)
	v_mfma_f32_32x32x16_bf16 v[64:79], v[150:153], v[154:157], v[64:79]
	ds_read_b128 v[150:153], v113 offset:4096
	v_cvt_pk_bf16_f32 v154, v16, v17
	v_cvt_pk_bf16_f32 v155, v18, v19
	v_cvt_pk_bf16_f32 v156, v20, v21
	v_cvt_pk_bf16_f32 v157, v22, v23
	s_waitcnt lgkmcnt(0)
	s_nop 0
	v_mfma_f32_32x32x16_bf16 v[64:79], v[150:153], v[154:157], v[64:79]
	ds_read_b128 v[150:153], v113 offset:5120
	v_cvt_pk_bf16_f32 v154, v24, v25
	v_cvt_pk_bf16_f32 v155, v26, v27
	v_cvt_pk_bf16_f32 v156, v28, v29
	v_cvt_pk_bf16_f32 v157, v30, v31
	s_waitcnt lgkmcnt(0)
	s_nop 0
	v_mfma_f32_32x32x16_bf16 v[64:79], v[150:153], v[154:157], v[64:79]
	ds_read_b128 v[150:153], v113 offset:6144
	v_cvt_pk_bf16_f32 v154, v0, v1
	v_cvt_pk_bf16_f32 v155, v2, v3
	v_cvt_pk_bf16_f32 v156, v4, v5
	v_cvt_pk_bf16_f32 v157, v6, v7
	s_waitcnt lgkmcnt(0)
	s_nop 0
	v_mfma_f32_32x32x16_bf16 v[64:79], v[150:153], v[154:157], v[64:79]
	ds_read_b128 v[150:153], v113 offset:7168
	v_cvt_pk_bf16_f32 v154, v8, v9
	v_cvt_pk_bf16_f32 v155, v10, v11
	v_cvt_pk_bf16_f32 v156, v12, v13
	v_cvt_pk_bf16_f32 v157, v14, v15
	s_waitcnt lgkmcnt(0)
	s_nop 0
	v_mfma_f32_32x32x16_bf16 v[64:79], v[150:153], v[154:157], v[64:79]
	s_nop 7
	s_nop 3
	v_add_f32_e32 v64, v148, v64
	v_mad_i32_i24 v162, v161, 0, v160
	global_store_dword v162, v64, s[34:35]
	v_add_f32_e32 v64, v147, v65
	v_mad_i32_i24 v163, v161, 1, v160
	global_store_dword v163, v64, s[34:35]
	v_add_f32_e32 v66, v144, v66
	v_mad_i32_i24 v164, v161, 2, v160
	global_store_dword v164, v66, s[34:35]
	v_add_f32_e32 v66, v142, v67
	v_mad_i32_i24 v165, v161, 3, v160
	global_store_dword v165, v66, s[34:35]
	v_add_f32_e32 v66, v140, v68
	v_mad_i32_i24 v162, v161, 8, v160
	global_store_dword v162, v66, s[34:35]
	v_add_f32_e32 v66, v138, v69
	v_mad_i32_i24 v163, v161, 9, v160
	global_store_dword v163, v66, s[34:35]
	v_add_f32_e32 v66, v137, v70
	v_mad_i32_i24 v164, v161, 10, v160
	global_store_dword v164, v66, s[34:35]
	v_add_f32_e32 v66, v146, v71
	v_mad_i32_i24 v165, v161, 11, v160
	global_store_dword v165, v66, s[34:35]
	v_add_f32_e32 v66, v145, v72
	v_mad_i32_i24 v162, v161, 16, v160
	global_store_dword v162, v66, s[34:35]
	v_add_f32_e32 v66, v143, v73
	v_mad_i32_i24 v163, v161, 17, v160
	global_store_dword v163, v66, s[34:35]
	v_add_f32_e32 v66, v141, v74
	v_mad_i32_i24 v164, v161, 18, v160
	global_store_dword v164, v66, s[34:35]
	v_add_f32_e32 v66, v139, v75
	v_mad_i32_i24 v165, v161, 19, v160
	global_store_dword v165, v66, s[34:35]
	v_add_f32_e32 v66, v136, v76
	v_mad_i32_i24 v162, v161, 24, v160
	global_store_dword v162, v66, s[34:35]
	v_add_f32_e32 v66, v135, v77
	v_mad_i32_i24 v163, v161, 25, v160
	global_store_dword v163, v66, s[34:35]
	v_add_f32_e32 v66, v133, v78
	v_mad_i32_i24 v164, v161, 26, v160
	global_store_dword v164, v66, s[34:35]
	v_not_b32_e32 v65, 27
	v_add_f32_e32 v66, v132, v79
	v_mad_i32_i24 v165, v161, 27, v160
	global_store_dword v165, v66, s[34:35]
	ds_read_b128 v[68:71], v114 offset:16384
	ds_read_b128 v[64:67], v114 offset:17408
	ds_read_b128 v[72:75], v115 offset:24576
	ds_read_b128 v[76:79], v115 offset:24608
	ds_read_b128 v[136:139], v115 offset:24640
	ds_read_b128 v[140:143], v115 offset:24672
	s_mov_b64 s[10:11], 0x200
	s_waitcnt lgkmcnt(0)
	v_pk_mul_f32 v[50:51], v[50:51], v[74:75]
	v_pk_mul_f32 v[48:49], v[48:49], v[72:73]
	ds_read_b128 v[72:75], v113 offset:8192
	v_pk_mul_f32 v[62:63], v[62:63], v[142:143]
	v_pk_mul_f32 v[58:59], v[58:59], v[138:139]
	v_pk_mul_f32 v[54:55], v[54:55], v[78:79]
	v_pk_mul_f32 v[60:61], v[60:61], v[140:141]
	v_pk_mul_f32 v[56:57], v[56:57], v[136:137]
	v_pk_mul_f32 v[52:53], v[52:53], v[76:77]
	v_lshl_add_u64 v[108:109], v[108:109], 0, s[10:11]
	s_waitcnt lgkmcnt(0)
; #define MFMA(a, b, c) __builtin_amdgcn_mfma_f32_32x32x16_bf16((a), (b), (c), 0, 0, 0)
; DI void hg_scan_block(const Params& p, int chain_in, unsigned char* smem) {
;     ...
;   for (int n = 0; n < 136; ++n) {
;     __syncthreads();
; #pragma unroll
;     for (int i = 0; i < 6; ++i) ((u32x4*)sU)[tid + 256 * i] = st[i];
;     if (tid < 128) s_ds[tid] = dsr;
;     __syncthreads();
;     if (n + 1 < 136) {
; #pragma unroll
;       for (int i = 0; i < 6; ++i) st[i] = src[(size_t)(n + 1) * 1536 + tid + 256 * i];
;       dsr = dsg[(size_t)(n + 1) * 128 + (tid & 127)];
;     }
;     ...
;     const bf16x8 v0 = ld16(s_vT + ((sl * 2 + 0) * 64 + lane) * 8), v1 = ld16(s_vT + ((sl * 2 + 1) * 64 + lane) * 8);
; #pragma unroll
;     for (int k = 0; k < 4; ++k) {
; #pragma unroll
;       for (int g = 0; g < 4; ++g) {
;         const f32x4 d4 = *(const f32x4*)(s_ds + 32 * k + 8 * g + 4 * h);
;         S[k][4 * g] *= d4[0]; S[k][4 * g + 1] *= d4[1]; S[k][4 * g + 2] *= d4[2]; S[k][4 * g + 3] *= d4[3];
;       }
;       S[k] = MFMA(ld16(s_khT + ((k * 2 + 0) * 64 + lane) * 8), v0, S[k]);
;       S[k] = MFMA(ld16(s_khT + ((k * 2 + 1) * 64 + lane) * 8), v1, S[k]);
;     }
; #pragma unroll
;     for (int r = 0; r < 16; ++r) oc[r] = on[r];
	v_mfma_f32_32x32x16_bf16 v[48:63], v[72:75], v[68:71], v[48:63]
	ds_read_b128 v[72:75], v113 offset:9216
	s_waitcnt lgkmcnt(0)
	v_mfma_f32_32x32x16_bf16 v[48:63], v[72:75], v[64:67], v[48:63]
	ds_read_b128 v[72:75], v115 offset:24704
	ds_read_b128 v[76:79], v115 offset:24736
	ds_read_b128 v[136:139], v115 offset:24768
	ds_read_b128 v[140:143], v115 offset:24800
	s_waitcnt lgkmcnt(3)
	v_pk_mul_f32 v[34:35], v[34:35], v[74:75]
	v_pk_mul_f32 v[32:33], v[32:33], v[72:73]
	ds_read_b128 v[72:75], v113 offset:10240
	s_waitcnt lgkmcnt(1)
	v_pk_mul_f32 v[46:47], v[46:47], v[142:143]
	v_pk_mul_f32 v[42:43], v[42:43], v[138:139]
	v_pk_mul_f32 v[38:39], v[38:39], v[78:79]
	v_pk_mul_f32 v[44:45], v[44:45], v[140:141]
	v_pk_mul_f32 v[40:41], v[40:41], v[136:137]
	v_pk_mul_f32 v[36:37], v[36:37], v[76:77]
	s_waitcnt lgkmcnt(0)
	s_nop 0
	v_mfma_f32_32x32x16_bf16 v[32:47], v[72:75], v[68:71], v[32:47]
	ds_read_b128 v[72:75], v113 offset:11264
	s_waitcnt lgkmcnt(0)
	v_mfma_f32_32x32x16_bf16 v[32:47], v[72:75], v[64:67], v[32:47]
	ds_read_b128 v[72:75], v115 offset:24832
	ds_read_b128 v[76:79], v115 offset:24864
	ds_read_b128 v[136:139], v115 offset:24896
	ds_read_b128 v[140:143], v115 offset:24928
	s_waitcnt lgkmcnt(3)
	v_pk_mul_f32 v[18:19], v[18:19], v[74:75]
	v_pk_mul_f32 v[16:17], v[16:17], v[72:73]
	ds_read_b128 v[72:75], v113 offset:12288
	s_waitcnt lgkmcnt(1)
	v_pk_mul_f32 v[30:31], v[30:31], v[142:143]
	v_pk_mul_f32 v[26:27], v[26:27], v[138:139]
	v_pk_mul_f32 v[22:23], v[22:23], v[78:79]
	v_pk_mul_f32 v[28:29], v[28:29], v[140:141]
	v_pk_mul_f32 v[24:25], v[24:25], v[136:137]
	v_pk_mul_f32 v[20:21], v[20:21], v[76:77]
	s_waitcnt lgkmcnt(0)
	s_nop 0
	v_mfma_f32_32x32x16_bf16 v[16:31], v[72:75], v[68:71], v[16:31]
	ds_read_b128 v[72:75], v113 offset:13312
	s_waitcnt lgkmcnt(0)
	v_mfma_f32_32x32x16_bf16 v[16:31], v[72:75], v[64:67], v[16:31]
	ds_read_b128 v[72:75], v115 offset:24960
	ds_read_b128 v[76:79], v115 offset:24992
	ds_read_b128 v[136:139], v115 offset:25024
	ds_read_b128 v[140:143], v115 offset:25056
	s_waitcnt lgkmcnt(3)
	v_pk_mul_f32 v[2:3], v[2:3], v[74:75]
	v_pk_mul_f32 v[0:1], v[0:1], v[72:73]
	ds_read_b128 v[72:75], v113 offset:14336
	s_waitcnt lgkmcnt(1)
	v_pk_mul_f32 v[14:15], v[14:15], v[142:143]
	v_pk_mul_f32 v[10:11], v[10:11], v[138:139]
	v_pk_mul_f32 v[6:7], v[6:7], v[78:79]
	v_pk_mul_f32 v[12:13], v[12:13], v[140:141]
	v_pk_mul_f32 v[8:9], v[8:9], v[136:137]
	v_pk_mul_f32 v[4:5], v[4:5], v[76:77]
	s_waitcnt lgkmcnt(0)
	v_mfma_f32_32x32x16_bf16 v[0:15], v[72:75], v[68:71], v[0:15]
	ds_read_b128 v[68:71], v113 offset:15360
	s_waitcnt lgkmcnt(0)
	v_mfma_f32_32x32x16_bf16 v[0:15], v[68:71], v[64:67], v[0:15]
	s_waitcnt vmcnt(16)
	v_mov_b32_e32 v132, v134
	v_mov_b32_e32 v133, v131
	v_mov_b32_e32 v135, v130
	v_mov_b32_e32 v145, v125
	v_mov_b32_e32 v146, v124
	v_mov_b32_e32 v144, v119
	v_mov_b32_e32 v147, v118
	v_mov_b32_e32 v148, v117
	v_mov_b32_e32 v136, v129
	v_mov_b32_e32 v139, v128
	v_mov_b32_e32 v141, v127
	v_mov_b32_e32 v143, v126
	v_mov_b32_e32 v137, v123
	v_mov_b32_e32 v138, v122
	v_mov_b32_e32 v140, v121
	v_mov_b32_e32 v142, v120
	v_xor_b32_e32 v113, 0x8000, v113
	v_xor_b32_e32 v114, 0x8000, v114
	v_xor_b32_e32 v115, 0x8000, v115
	v_xor_b32_e32 v116, 0x8000, v116
	s_cbranch_scc0 .LBB0_504
.LBB0_498:
	s_waitcnt vmcnt(0)
	s_and_saveexec_b64 s[10:11], s[4:5]
	ds_write_b32 v116, v111 offset:24576
	s_or_b64 exec, exec, s[10:11]
	s_cmp_lg_u32 s8, 0x32a000
	s_cselect_b64 s[10:11], -1, 0
	s_cmp_eq_u32 s8, 0x32a000
	s_waitcnt lgkmcnt(0)
	s_barrier
	s_cbranch_scc1 .LBB0_502
	v_lshl_add_u64 v[64:65], v[104:105], 0, s[8:9]
	s_add_i32 s29, s39, s38
	s_xor_b32 s39, s39, 0x8000
	s_mov_b32 s28, s29
	v_add_co_u32_e32 v66, vcc, 0x619d5600, v64
	s_mov_b32 m0, s28
	s_nop 0
	v_addc_co_u32_e32 v67, vcc, 0, v65, vcc
	global_load_lds_dwordx4 v[66:67], off
	s_add_i32 s28, s29, 0x1000
	v_add_co_u32_e32 v66, vcc, 0x619d6600, v64
	s_mov_b32 m0, s28
	s_nop 0
	v_addc_co_u32_e32 v67, vcc, 0, v65, vcc
	global_load_lds_dwordx4 v[66:67], off
	s_add_i32 s28, s29, 0x2000
	v_add_co_u32_e32 v66, vcc, 0x619d7600, v64
	s_mov_b32 m0, s28
	s_nop 0
	v_addc_co_u32_e32 v67, vcc, 0, v65, vcc
	global_load_lds_dwordx4 v[66:67], off
	s_add_i32 s28, s29, 0x3000
	v_add_co_u32_e32 v66, vcc, 0x619d8600, v64
	s_mov_b32 m0, s28
	s_nop 0
	v_addc_co_u32_e32 v67, vcc, 0, v65, vcc
	global_load_lds_dwordx4 v[66:67], off
	s_add_i32 s28, s29, 0x4000
	v_add_co_u32_e32 v66, vcc, 0x619d9600, v64
	s_mov_b32 m0, s28
	s_nop 0
	v_addc_co_u32_e32 v67, vcc, 0, v65, vcc
	global_load_lds_dwordx4 v[66:67], off
	s_add_i32 s28, s29, 0x5000
	v_add_co_u32_e32 v66, vcc, 0x619da600, v64
	s_mov_b32 m0, s28
	s_nop 0
	v_addc_co_u32_e32 v67, vcc, 0, v65, vcc
	global_load_lds_dwordx4 v[66:67], off
	global_load_dword v111, v[108:109], off
